# one static s_setprio 1 for waves 4-7 at kernel entry (all per-phase priority toggles already deleted)
# baseline (speedup 1.0000x reference)
; #define LAS __attribute__((address_space(3)))
; __global__ void __launch_bounds__(512, 2) fwd_kernel(Args a_byval) {
;     ...
;     const int tid = threadIdx.x, lane = tid & 63, wave = __builtin_amdgcn_readfirstlane(tid >> 6);
;     const int G = gridDim.x, bx = blockIdx.x;
;     const int lo = kp->ph_lo, hi = kp->ph_hi;
;     unsigned char* ws = kp->ws;
;     ...
;     volatile LAS unsigned* MISC = (volatile LAS unsigned*)(lds + RING_BYTES + 8192);
;     if (tid < 4) MISC[tid] = 0u;
;     __syncthreads();
;     XcdBarrier bar; bar.bar = (unsigned*)(ws + WS_BAR); bar.x = 0; bar.st = MISC;
;     if (hi - lo > 1 || lo == 3) bar = xcd_barrier_post((unsigned*)(ws + WS_BAR), MISC);
_Z10fwd_kernel4Args:
	s_load_dwordx4 s[36:39], s[0:1], 0xb0
	s_load_dword s3, s[0:1], 0xc0
	s_add_u32 s4, s0, 0xc0
	v_and_b32_e32 v226, 0x3ff, v0
	v_cmp_gt_u32_e32 vcc, 4, v226
	v_readfirstlane_b32 s19, v226
	s_waitcnt lgkmcnt(0)
	v_writelane_b32 v253, s3, 0
	v_writelane_b32 v253, s0, 1
	s_addc_u32 s5, s1, 0
	s_nop 0
	v_writelane_b32 v253, s1, 2
	v_writelane_b32 v253, s4, 3
	s_nop 1
	v_writelane_b32 v253, s5, 4
	s_and_saveexec_b64 s[0:1], vcc
	v_lshl_add_u32 v1, v226, 2, 0
	v_add_u32_e32 v1, 0x22000, v1
	v_mov_b32_e32 v2, 0
	ds_write_b32 v1, v2
	s_or_b64 exec, exec, s[0:1]
	s_cmpk_ge_u32 s19, 0x100
	s_cbranch_scc0 .Lprio_done
	s_setprio 1
.Lprio_done:
	s_add_u32 s40, s36, 0x4000
	s_addc_u32 s41, s37, 0
	s_sub_i32 s0, s39, s38
	s_cmp_lt_i32 s0, 2
	s_cselect_b64 s[0:1], -1, 0
	s_cmp_lg_u32 s38, 3
	s_cselect_b64 s[4:5], -1, 0
	s_and_b64 s[0:1], s[4:5], s[0:1]
	s_mov_b32 s3, 0
	s_and_b64 vcc, exec, s[0:1]
	s_waitcnt lgkmcnt(0)
	s_barrier
	s_cbranch_vccnz .LBB0_7
	s_getreg_b32 s0, hwreg(HW_REG_XCC_ID, 0, 4)
	s_and_b32 s3, s0, 15
	v_cmp_eq_u32_e32 vcc, 0, v226
	s_and_saveexec_b64 s[0:1], vcc
	s_cbranch_execz .LBB0_6
	s_mov_b64 s[4:5], exec
	v_mbcnt_lo_u32_b32 v1, s4, 0
	v_mbcnt_hi_u32_b32 v1, s5, v1
	v_cmp_eq_u32_e32 vcc, 0, v1
	s_and_b64 s[6:7], exec, vcc
	s_mov_b64 exec, s[6:7]
	s_cbranch_execz .LBB0_6
	s_lshl_b32 s6, s3, 8
	s_bcnt1_i32_b64 s4, s[4:5]
	v_mov_b32_e32 v1, s6
	v_mov_b32_e32 v2, s4
	global_atomic_add v1, v2, s[40:41] offset:1024
